# v9 + m1 gate epilogue: drop 15 redundant vmcnt(0) waits that serialized the sigmoid blocks behind each store
# baseline (speedup 1.0000x reference)
; __device__ __forceinline__ float sigmoidf_(float x) { return rcpf_(1.f + ex2(-x * LOG2E)); }
;     __device__ __forceinline__ void operator()(const f32x4 (&acc)[2][2][4][2], const Unit& u, int wr, int wc, int fr, int fq) const {
;     ...
;                 for (int bj = 0; bj < 2; ++bj) { f32x4 v0 = acc[ai][bj][m][0], v1 = acc[ai][bj][m][1];
;                     if (gate) {
; #pragma unroll
;                         for (int j = 0; j < 4; ++j) { v0[j] = sigmoidf_(v0[j] + gb[bj][0][j]); v1[j] = sigmoidf_(v1[j] + gb[bj][1][j]); } }
.LBB0_150:
	s_andn2_b64 vcc, exec, s[24:25]
	s_cbranch_vccnz .LBB0_152
	v_add_f32_e32 v134, v134, v62
	v_add_f32_e32 v130, v130, v58
	v_add_f32_e32 v135, v135, v63
	v_add_f32_e32 v131, v131, v59
	v_add_f32_e32 v136, v136, v64
	v_add_f32_e32 v132, v132, v60
	v_add_f32_e32 v137, v137, v65
	v_add_f32_e32 v133, v133, v61
	v_mul_f32_e32 v134, 0xbfb8aa3b, v134
	v_mul_f32_e32 v130, 0xbfb8aa3b, v130
	v_mul_f32_e32 v135, 0xbfb8aa3b, v135
	v_mul_f32_e32 v131, 0xbfb8aa3b, v131
	v_mul_f32_e32 v136, 0xbfb8aa3b, v136
	v_mul_f32_e32 v132, 0xbfb8aa3b, v132
	v_mul_f32_e32 v137, 0xbfb8aa3b, v137
	v_mul_f32_e32 v133, 0xbfb8aa3b, v133
	v_exp_f32_e32 v134, v134
	v_exp_f32_e32 v130, v130
	v_exp_f32_e32 v135, v135
	v_exp_f32_e32 v131, v131
	v_exp_f32_e32 v136, v136
	v_exp_f32_e32 v132, v132
	v_exp_f32_e32 v137, v137
	v_exp_f32_e32 v133, v133
	v_add_f32_e32 v134, 1.0, v134
	v_add_f32_e32 v130, 1.0, v130
	v_add_f32_e32 v135, 1.0, v135
	v_add_f32_e32 v131, 1.0, v131
	v_add_f32_e32 v136, 1.0, v136
	v_add_f32_e32 v132, 1.0, v132
	v_add_f32_e32 v137, 1.0, v137
	v_add_f32_e32 v133, 1.0, v133
	v_rcp_f32_e32 v134, v134
	v_rcp_f32_e32 v130, v130
	v_rcp_f32_e32 v135, v135
	v_rcp_f32_e32 v131, v131
	v_rcp_f32_e32 v136, v136
	v_rcp_f32_e32 v132, v132
	v_rcp_f32_e32 v137, v137
	v_rcp_f32_e32 v133, v133

; __device__ __forceinline__ float sigmoidf_(float x) { return rcpf_(1.f + ex2(-x * LOG2E)); }
;     __device__ __forceinline__ void operator()(const f32x4 (&acc)[2][2][4][2], const Unit& u, int wr, int wc, int fr, int fq) const {
;     ...
;                 for (int bj = 0; bj < 2; ++bj) { f32x4 v0 = acc[ai][bj][m][0], v1 = acc[ai][bj][m][1];
;                     if (gate) {
; #pragma unroll
;                         for (int j = 0; j < 4; ++j) { v0[j] = sigmoidf_(v0[j] + gb[bj][0][j]); v1[j] = sigmoidf_(v1[j] + gb[bj][1][j]); } }
.LBB0_159:
	v_add_f32_e32 v126, v126, v78
	v_add_f32_e32 v122, v122, v74
	v_add_f32_e32 v127, v127, v79
	v_add_f32_e32 v123, v123, v75
	v_add_f32_e32 v128, v128, v80
	v_add_f32_e32 v124, v124, v76
	v_add_f32_e32 v129, v129, v81
	v_add_f32_e32 v125, v125, v77
	v_mul_f32_e32 v126, 0xbfb8aa3b, v126
	v_mul_f32_e32 v122, 0xbfb8aa3b, v122
	v_mul_f32_e32 v127, 0xbfb8aa3b, v127
	v_mul_f32_e32 v123, 0xbfb8aa3b, v123
	v_mul_f32_e32 v128, 0xbfb8aa3b, v128
	v_mul_f32_e32 v124, 0xbfb8aa3b, v124
	v_mul_f32_e32 v129, 0xbfb8aa3b, v129
	v_mul_f32_e32 v125, 0xbfb8aa3b, v125
	v_exp_f32_e32 v126, v126
	v_exp_f32_e32 v122, v122
	v_exp_f32_e32 v127, v127
	v_exp_f32_e32 v123, v123
	v_exp_f32_e32 v128, v128
	v_exp_f32_e32 v124, v124
	v_exp_f32_e32 v129, v129
	v_exp_f32_e32 v125, v125
	v_add_f32_e32 v126, 1.0, v126
	v_add_f32_e32 v122, 1.0, v122
	v_add_f32_e32 v127, 1.0, v127
	v_add_f32_e32 v123, 1.0, v123
	v_add_f32_e32 v128, 1.0, v128
	v_add_f32_e32 v124, 1.0, v124
	v_add_f32_e32 v129, 1.0, v129
	v_add_f32_e32 v125, 1.0, v125
	v_rcp_f32_e32 v126, v126
	v_rcp_f32_e32 v122, v122
	v_rcp_f32_e32 v127, v127
	v_rcp_f32_e32 v123, v123
	v_rcp_f32_e32 v128, v128
	v_rcp_f32_e32 v124, v124
	v_rcp_f32_e32 v129, v129
	v_rcp_f32_e32 v125, v125

; __device__ __forceinline__ float sigmoidf_(float x) { return rcpf_(1.f + ex2(-x * LOG2E)); }
;     __device__ __forceinline__ void operator()(const f32x4 (&acc)[2][2][4][2], const Unit& u, int wr, int wc, int fr, int fq) const {
;     ...
;                 for (int bj = 0; bj < 2; ++bj) { f32x4 v0 = acc[ai][bj][m][0], v1 = acc[ai][bj][m][1];
;                     if (gate) {
; #pragma unroll
;                         for (int j = 0; j < 4; ++j) { v0[j] = sigmoidf_(v0[j] + gb[bj][0][j]); v1[j] = sigmoidf_(v1[j] + gb[bj][1][j]); } }
.LBB0_162:
	s_andn2_b64 vcc, exec, s[24:25]
	s_cbranch_vccnz .LBB0_164
	v_add_f32_e32 v118, v118, v62
	v_add_f32_e32 v114, v114, v58
	v_add_f32_e32 v119, v119, v63
	v_add_f32_e32 v115, v115, v59
	v_add_f32_e32 v120, v120, v64
	v_add_f32_e32 v116, v116, v60
	v_add_f32_e32 v121, v121, v65
	v_add_f32_e32 v117, v117, v61
	v_mul_f32_e32 v118, 0xbfb8aa3b, v118
	v_mul_f32_e32 v114, 0xbfb8aa3b, v114
	v_mul_f32_e32 v119, 0xbfb8aa3b, v119
	v_mul_f32_e32 v115, 0xbfb8aa3b, v115
	v_mul_f32_e32 v120, 0xbfb8aa3b, v120
	v_mul_f32_e32 v116, 0xbfb8aa3b, v116
	v_mul_f32_e32 v121, 0xbfb8aa3b, v121
	v_mul_f32_e32 v117, 0xbfb8aa3b, v117
	v_exp_f32_e32 v118, v118
	v_exp_f32_e32 v114, v114
	v_exp_f32_e32 v119, v119
	v_exp_f32_e32 v115, v115
	v_exp_f32_e32 v120, v120
	v_exp_f32_e32 v116, v116
	v_exp_f32_e32 v121, v121
	v_exp_f32_e32 v117, v117
	v_add_f32_e32 v118, 1.0, v118
	v_add_f32_e32 v114, 1.0, v114
	v_add_f32_e32 v119, 1.0, v119
	v_add_f32_e32 v115, 1.0, v115
	v_add_f32_e32 v120, 1.0, v120
	v_add_f32_e32 v116, 1.0, v116
	v_add_f32_e32 v121, 1.0, v121
	v_add_f32_e32 v117, 1.0, v117
	v_rcp_f32_e32 v118, v118
	v_rcp_f32_e32 v114, v114
	v_rcp_f32_e32 v119, v119
	v_rcp_f32_e32 v115, v115
	v_rcp_f32_e32 v120, v120
	v_rcp_f32_e32 v116, v116
	v_rcp_f32_e32 v121, v121
	v_rcp_f32_e32 v117, v117

; __device__ __forceinline__ float sigmoidf_(float x) { return rcpf_(1.f + ex2(-x * LOG2E)); }
;     __device__ __forceinline__ void operator()(const f32x4 (&acc)[2][2][4][2], const Unit& u, int wr, int wc, int fr, int fq) const {
;     ...
;                 for (int bj = 0; bj < 2; ++bj) { f32x4 v0 = acc[ai][bj][m][0], v1 = acc[ai][bj][m][1];
;                     if (gate) {
; #pragma unroll
;                         for (int j = 0; j < 4; ++j) { v0[j] = sigmoidf_(v0[j] + gb[bj][0][j]); v1[j] = sigmoidf_(v1[j] + gb[bj][1][j]); } }
.LBB0_171:
	v_add_f32_e32 v110, v110, v78
	v_add_f32_e32 v106, v106, v74
	v_add_f32_e32 v111, v111, v79
	v_add_f32_e32 v107, v107, v75
	v_add_f32_e32 v112, v112, v80
	v_add_f32_e32 v108, v108, v76
	v_add_f32_e32 v113, v113, v81
	v_add_f32_e32 v109, v109, v77
	v_mul_f32_e32 v110, 0xbfb8aa3b, v110
	v_mul_f32_e32 v106, 0xbfb8aa3b, v106
	v_mul_f32_e32 v111, 0xbfb8aa3b, v111
	v_mul_f32_e32 v107, 0xbfb8aa3b, v107
	v_mul_f32_e32 v112, 0xbfb8aa3b, v112
	v_mul_f32_e32 v108, 0xbfb8aa3b, v108
	v_mul_f32_e32 v113, 0xbfb8aa3b, v113
	v_mul_f32_e32 v109, 0xbfb8aa3b, v109
	v_exp_f32_e32 v110, v110
	v_exp_f32_e32 v106, v106
	v_exp_f32_e32 v111, v111
	v_exp_f32_e32 v107, v107
	v_exp_f32_e32 v112, v112
	v_exp_f32_e32 v108, v108
	v_exp_f32_e32 v113, v113
	v_exp_f32_e32 v109, v109
	v_add_f32_e32 v110, 1.0, v110
	v_add_f32_e32 v106, 1.0, v106
	v_add_f32_e32 v111, 1.0, v111
	v_add_f32_e32 v107, 1.0, v107
	v_add_f32_e32 v112, 1.0, v112
	v_add_f32_e32 v108, 1.0, v108
	v_add_f32_e32 v113, 1.0, v113
	v_add_f32_e32 v109, 1.0, v109
	v_rcp_f32_e32 v110, v110
	v_rcp_f32_e32 v106, v106
	v_rcp_f32_e32 v111, v111
	v_rcp_f32_e32 v107, v107
	v_rcp_f32_e32 v112, v112
	v_rcp_f32_e32 v108, v108
	v_rcp_f32_e32 v113, v113
	v_rcp_f32_e32 v109, v109

; __device__ __forceinline__ float sigmoidf_(float x) { return rcpf_(1.f + ex2(-x * LOG2E)); }
;     __device__ __forceinline__ void operator()(const f32x4 (&acc)[2][2][4][2], const Unit& u, int wr, int wc, int fr, int fq) const {
;     ...
;                 for (int bj = 0; bj < 2; ++bj) { f32x4 v0 = acc[ai][bj][m][0], v1 = acc[ai][bj][m][1];
;                     if (gate) {
; #pragma unroll
;                         for (int j = 0; j < 4; ++j) { v0[j] = sigmoidf_(v0[j] + gb[bj][0][j]); v1[j] = sigmoidf_(v1[j] + gb[bj][1][j]); } }
.LBB0_174:
	s_andn2_b64 vcc, exec, s[24:25]
	s_cbranch_vccnz .LBB0_176
	v_add_f32_e32 v102, v102, v62
	v_add_f32_e32 v98, v98, v58
	v_add_f32_e32 v103, v103, v63
	v_add_f32_e32 v99, v99, v59
	v_add_f32_e32 v104, v104, v64
	v_add_f32_e32 v100, v100, v60
	v_add_f32_e32 v105, v105, v65
	v_add_f32_e32 v101, v101, v61
	v_mul_f32_e32 v102, 0xbfb8aa3b, v102
	v_mul_f32_e32 v98, 0xbfb8aa3b, v98
	v_mul_f32_e32 v103, 0xbfb8aa3b, v103
	v_mul_f32_e32 v99, 0xbfb8aa3b, v99
	v_mul_f32_e32 v104, 0xbfb8aa3b, v104
	v_mul_f32_e32 v100, 0xbfb8aa3b, v100
	v_mul_f32_e32 v105, 0xbfb8aa3b, v105
	v_mul_f32_e32 v101, 0xbfb8aa3b, v101
	v_exp_f32_e32 v102, v102
	v_exp_f32_e32 v98, v98
	v_exp_f32_e32 v103, v103
	v_exp_f32_e32 v99, v99
	v_exp_f32_e32 v104, v104
	v_exp_f32_e32 v100, v100
	v_exp_f32_e32 v105, v105
	v_exp_f32_e32 v101, v101
	v_add_f32_e32 v102, 1.0, v102
	v_add_f32_e32 v98, 1.0, v98
	v_add_f32_e32 v103, 1.0, v103
	v_add_f32_e32 v99, 1.0, v99
	v_add_f32_e32 v104, 1.0, v104
	v_add_f32_e32 v100, 1.0, v100
	v_add_f32_e32 v105, 1.0, v105
	v_add_f32_e32 v101, 1.0, v101
	v_rcp_f32_e32 v102, v102
	v_rcp_f32_e32 v98, v98
	v_rcp_f32_e32 v103, v103
	v_rcp_f32_e32 v99, v99
	v_rcp_f32_e32 v104, v104
	v_rcp_f32_e32 v100, v100
	v_rcp_f32_e32 v105, v105
	v_rcp_f32_e32 v101, v101

; __device__ __forceinline__ float sigmoidf_(float x) { return rcpf_(1.f + ex2(-x * LOG2E)); }
;     __device__ __forceinline__ void operator()(const f32x4 (&acc)[2][2][4][2], const Unit& u, int wr, int wc, int fr, int fq) const {
;     ...
;                 for (int bj = 0; bj < 2; ++bj) { f32x4 v0 = acc[ai][bj][m][0], v1 = acc[ai][bj][m][1];
;                     if (gate) {
; #pragma unroll
;                         for (int j = 0; j < 4; ++j) { v0[j] = sigmoidf_(v0[j] + gb[bj][0][j]); v1[j] = sigmoidf_(v1[j] + gb[bj][1][j]); } }
.LBB0_183:
	v_add_f32_e32 v94, v94, v78
	v_add_f32_e32 v90, v90, v74
	v_add_f32_e32 v95, v95, v79
	v_add_f32_e32 v91, v91, v75
	v_add_f32_e32 v96, v96, v80
	v_add_f32_e32 v92, v92, v76
	v_add_f32_e32 v97, v97, v81
	v_add_f32_e32 v93, v93, v77
	v_mul_f32_e32 v94, 0xbfb8aa3b, v94
	v_mul_f32_e32 v90, 0xbfb8aa3b, v90
	v_mul_f32_e32 v95, 0xbfb8aa3b, v95
	v_mul_f32_e32 v91, 0xbfb8aa3b, v91
	v_mul_f32_e32 v96, 0xbfb8aa3b, v96
	v_mul_f32_e32 v92, 0xbfb8aa3b, v92
	v_mul_f32_e32 v97, 0xbfb8aa3b, v97
	v_mul_f32_e32 v93, 0xbfb8aa3b, v93
	v_exp_f32_e32 v94, v94
	v_exp_f32_e32 v90, v90
	v_exp_f32_e32 v95, v95
	v_exp_f32_e32 v91, v91
	v_exp_f32_e32 v96, v96
	v_exp_f32_e32 v92, v92
	v_exp_f32_e32 v97, v97
	v_exp_f32_e32 v93, v93
	v_add_f32_e32 v94, 1.0, v94
	v_add_f32_e32 v90, 1.0, v90
	v_add_f32_e32 v95, 1.0, v95
	v_add_f32_e32 v91, 1.0, v91
	v_add_f32_e32 v96, 1.0, v96
	v_add_f32_e32 v92, 1.0, v92
	v_add_f32_e32 v97, 1.0, v97
	v_add_f32_e32 v93, 1.0, v93
	v_rcp_f32_e32 v94, v94
	v_rcp_f32_e32 v90, v90
	v_rcp_f32_e32 v95, v95
	v_rcp_f32_e32 v91, v91
	v_rcp_f32_e32 v96, v96
	v_rcp_f32_e32 v92, v92
	v_rcp_f32_e32 v97, v97
	v_rcp_f32_e32 v93, v93

; __device__ __forceinline__ float sigmoidf_(float x) { return rcpf_(1.f + ex2(-x * LOG2E)); }
;     __device__ __forceinline__ void operator()(const f32x4 (&acc)[2][2][4][2], const Unit& u, int wr, int wc, int fr, int fq) const {
;     ...
;                 for (int bj = 0; bj < 2; ++bj) { f32x4 v0 = acc[ai][bj][m][0], v1 = acc[ai][bj][m][1];
;                     if (gate) {
; #pragma unroll
;                         for (int j = 0; j < 4; ++j) { v0[j] = sigmoidf_(v0[j] + gb[bj][0][j]); v1[j] = sigmoidf_(v1[j] + gb[bj][1][j]); } }
.LBB0_186:
	s_andn2_b64 vcc, exec, s[24:25]
	s_cbranch_vccnz .LBB0_188
	v_add_f32_e32 v86, v86, v62
	v_add_f32_e32 v82, v82, v58
	v_add_f32_e32 v87, v87, v63
	v_add_f32_e32 v83, v83, v59
	v_add_f32_e32 v88, v88, v64
	v_add_f32_e32 v84, v84, v60
	v_add_f32_e32 v89, v89, v65
	v_add_f32_e32 v85, v85, v61
	v_mul_f32_e32 v86, 0xbfb8aa3b, v86
	v_mul_f32_e32 v82, 0xbfb8aa3b, v82
	v_mul_f32_e32 v87, 0xbfb8aa3b, v87
	v_mul_f32_e32 v83, 0xbfb8aa3b, v83
	v_mul_f32_e32 v88, 0xbfb8aa3b, v88
	v_mul_f32_e32 v84, 0xbfb8aa3b, v84
	v_mul_f32_e32 v89, 0xbfb8aa3b, v89
	v_mul_f32_e32 v85, 0xbfb8aa3b, v85
	v_exp_f32_e32 v86, v86
	v_exp_f32_e32 v82, v82
	v_exp_f32_e32 v87, v87
	v_exp_f32_e32 v83, v83
	v_exp_f32_e32 v88, v88
	v_exp_f32_e32 v84, v84
	v_exp_f32_e32 v89, v89
	v_exp_f32_e32 v85, v85
	v_add_f32_e32 v86, 1.0, v86
	v_add_f32_e32 v82, 1.0, v82
	v_add_f32_e32 v87, 1.0, v87
	v_add_f32_e32 v83, 1.0, v83
	v_add_f32_e32 v88, 1.0, v88
	v_add_f32_e32 v84, 1.0, v84
	v_add_f32_e32 v89, 1.0, v89
	v_add_f32_e32 v85, 1.0, v85
	v_rcp_f32_e32 v86, v86
	v_rcp_f32_e32 v82, v82
	v_rcp_f32_e32 v87, v87
	v_rcp_f32_e32 v83, v83
	v_rcp_f32_e32 v88, v88
	v_rcp_f32_e32 v84, v84
	v_rcp_f32_e32 v89, v89
	v_rcp_f32_e32 v85, v85

; __device__ __forceinline__ float sigmoidf_(float x) { return rcpf_(1.f + ex2(-x * LOG2E)); }
;     __device__ __forceinline__ void operator()(const f32x4 (&acc)[2][2][4][2], const Unit& u, int wr, int wc, int fr, int fq) const {
;     ...
;                 for (int bj = 0; bj < 2; ++bj) { f32x4 v0 = acc[ai][bj][m][0], v1 = acc[ai][bj][m][1];
;                     if (gate) {
; #pragma unroll
;                         for (int j = 0; j < 4; ++j) { v0[j] = sigmoidf_(v0[j] + gb[bj][0][j]); v1[j] = sigmoidf_(v1[j] + gb[bj][1][j]); } }
.LBB0_195:
	v_add_f32_e32 v70, v70, v78
	v_add_f32_e32 v66, v66, v74
	v_add_f32_e32 v71, v71, v79
	v_add_f32_e32 v67, v67, v75
	v_add_f32_e32 v72, v72, v80
	v_add_f32_e32 v68, v68, v76
	v_add_f32_e32 v73, v73, v81
	v_add_f32_e32 v69, v69, v77
	v_mul_f32_e32 v70, 0xbfb8aa3b, v70
	v_mul_f32_e32 v66, 0xbfb8aa3b, v66
	v_mul_f32_e32 v71, 0xbfb8aa3b, v71
	v_mul_f32_e32 v67, 0xbfb8aa3b, v67
	v_mul_f32_e32 v72, 0xbfb8aa3b, v72
	v_mul_f32_e32 v68, 0xbfb8aa3b, v68
	v_mul_f32_e32 v73, 0xbfb8aa3b, v73
	v_mul_f32_e32 v69, 0xbfb8aa3b, v69
	v_exp_f32_e32 v70, v70
	v_exp_f32_e32 v66, v66
	v_exp_f32_e32 v71, v71
	v_exp_f32_e32 v67, v67
	v_exp_f32_e32 v72, v72
	v_exp_f32_e32 v68, v68
	v_exp_f32_e32 v73, v73
	v_exp_f32_e32 v69, v69
	v_add_f32_e32 v70, 1.0, v70
	v_add_f32_e32 v66, 1.0, v66
	v_add_f32_e32 v71, 1.0, v71
	v_add_f32_e32 v67, 1.0, v67
	v_add_f32_e32 v72, 1.0, v72
	v_add_f32_e32 v68, 1.0, v68
	v_add_f32_e32 v73, 1.0, v73
	v_add_f32_e32 v69, 1.0, v69
	v_rcp_f32_e32 v70, v70
	v_rcp_f32_e32 v66, v66
	v_rcp_f32_e32 v71, v71
	v_rcp_f32_e32 v67, v67
	v_rcp_f32_e32 v72, v72
	v_rcp_f32_e32 v68, v68
	v_rcp_f32_e32 v73, v73
	v_rcp_f32_e32 v69, v69

; __device__ __forceinline__ float sigmoidf_(float x) { return rcpf_(1.f + ex2(-x * LOG2E)); }
;     __device__ __forceinline__ void operator()(const f32x4 (&acc)[2][2][4][2], const Unit& u, int wr, int wc, int fr, int fq) const {
;     ...
;                 for (int bj = 0; bj < 2; ++bj) { f32x4 v0 = acc[ai][bj][m][0], v1 = acc[ai][bj][m][1];
;                     if (gate) {
; #pragma unroll
;                         for (int j = 0; j < 4; ++j) { v0[j] = sigmoidf_(v0[j] + gb[bj][0][j]); v1[j] = sigmoidf_(v1[j] + gb[bj][1][j]); } }
.LBB0_198:
	s_andn2_b64 vcc, exec, s[24:25]
	s_cbranch_vccnz .LBB0_200
	v_add_f32_e32 v54, v54, v62
	v_add_f32_e32 v50, v50, v58
	v_add_f32_e32 v55, v55, v63
	v_add_f32_e32 v51, v51, v59
	v_add_f32_e32 v56, v56, v64
	v_add_f32_e32 v52, v52, v60
	v_add_f32_e32 v57, v57, v65
	v_add_f32_e32 v53, v53, v61
	v_mul_f32_e32 v54, 0xbfb8aa3b, v54
	v_mul_f32_e32 v50, 0xbfb8aa3b, v50
	v_mul_f32_e32 v55, 0xbfb8aa3b, v55
	v_mul_f32_e32 v51, 0xbfb8aa3b, v51
	v_mul_f32_e32 v56, 0xbfb8aa3b, v56
	v_mul_f32_e32 v52, 0xbfb8aa3b, v52
	v_mul_f32_e32 v57, 0xbfb8aa3b, v57
	v_mul_f32_e32 v53, 0xbfb8aa3b, v53
	v_exp_f32_e32 v54, v54
	v_exp_f32_e32 v50, v50
	v_exp_f32_e32 v55, v55
	v_exp_f32_e32 v51, v51
	v_exp_f32_e32 v56, v56
	v_exp_f32_e32 v52, v52
	v_exp_f32_e32 v57, v57
	v_exp_f32_e32 v53, v53
	v_add_f32_e32 v54, 1.0, v54
	v_add_f32_e32 v50, 1.0, v50
	v_add_f32_e32 v55, 1.0, v55
	v_add_f32_e32 v51, 1.0, v51
	v_add_f32_e32 v56, 1.0, v56
	v_add_f32_e32 v52, 1.0, v52
	v_add_f32_e32 v57, 1.0, v57
	v_add_f32_e32 v53, 1.0, v53
	v_rcp_f32_e32 v54, v54
	v_rcp_f32_e32 v50, v50
	v_rcp_f32_e32 v55, v55
	v_rcp_f32_e32 v51, v51
	v_rcp_f32_e32 v56, v56
	v_rcp_f32_e32 v52, v52
	v_rcp_f32_e32 v57, v57
	v_rcp_f32_e32 v53, v53

; __device__ __forceinline__ float sigmoidf_(float x) { return rcpf_(1.f + ex2(-x * LOG2E)); }
;     __device__ __forceinline__ void operator()(const f32x4 (&acc)[2][2][4][2], const Unit& u, int wr, int wc, int fr, int fq) const {
;     ...
;                 for (int bj = 0; bj < 2; ++bj) { f32x4 v0 = acc[ai][bj][m][0], v1 = acc[ai][bj][m][1];
;                     if (gate) {
; #pragma unroll
;                         for (int j = 0; j < 4; ++j) { v0[j] = sigmoidf_(v0[j] + gb[bj][0][j]); v1[j] = sigmoidf_(v1[j] + gb[bj][1][j]); } }
.LBB0_207:
	v_add_f32_e32 v46, v46, v78
	v_add_f32_e32 v42, v42, v74
	v_add_f32_e32 v47, v47, v79
	v_add_f32_e32 v43, v43, v75
	v_add_f32_e32 v48, v48, v80
	v_add_f32_e32 v44, v44, v76
	v_add_f32_e32 v49, v49, v81
	v_add_f32_e32 v45, v45, v77
	v_mul_f32_e32 v46, 0xbfb8aa3b, v46
	v_mul_f32_e32 v42, 0xbfb8aa3b, v42
	v_mul_f32_e32 v47, 0xbfb8aa3b, v47
	v_mul_f32_e32 v43, 0xbfb8aa3b, v43
	v_mul_f32_e32 v48, 0xbfb8aa3b, v48
	v_mul_f32_e32 v44, 0xbfb8aa3b, v44
	v_mul_f32_e32 v49, 0xbfb8aa3b, v49
	v_mul_f32_e32 v45, 0xbfb8aa3b, v45
	v_exp_f32_e32 v46, v46
	v_exp_f32_e32 v42, v42
	v_exp_f32_e32 v47, v47
	v_exp_f32_e32 v43, v43
	v_exp_f32_e32 v48, v48
	v_exp_f32_e32 v44, v44
	v_exp_f32_e32 v49, v49
	v_exp_f32_e32 v45, v45
	v_add_f32_e32 v46, 1.0, v46
	v_add_f32_e32 v42, 1.0, v42
	v_add_f32_e32 v47, 1.0, v47
	v_add_f32_e32 v43, 1.0, v43
	v_add_f32_e32 v48, 1.0, v48
	v_add_f32_e32 v44, 1.0, v44
	v_add_f32_e32 v49, 1.0, v49
	v_add_f32_e32 v45, 1.0, v45
	v_rcp_f32_e32 v46, v46
	v_rcp_f32_e32 v42, v42
	v_rcp_f32_e32 v47, v47
	v_rcp_f32_e32 v43, v43
	v_rcp_f32_e32 v48, v48
	v_rcp_f32_e32 v44, v44
	v_rcp_f32_e32 v49, v49
	v_rcp_f32_e32 v45, v45

; __device__ __forceinline__ float sigmoidf_(float x) { return rcpf_(1.f + ex2(-x * LOG2E)); }
;     __device__ __forceinline__ void operator()(const f32x4 (&acc)[2][2][4][2], const Unit& u, int wr, int wc, int fr, int fq) const {
;     ...
;                 for (int bj = 0; bj < 2; ++bj) { f32x4 v0 = acc[ai][bj][m][0], v1 = acc[ai][bj][m][1];
;                     if (gate) {
; #pragma unroll
;                         for (int j = 0; j < 4; ++j) { v0[j] = sigmoidf_(v0[j] + gb[bj][0][j]); v1[j] = sigmoidf_(v1[j] + gb[bj][1][j]); } }
.LBB0_210:
	s_andn2_b64 vcc, exec, s[24:25]
	s_cbranch_vccnz .LBB0_212
	v_add_f32_e32 v38, v38, v62
	v_add_f32_e32 v34, v34, v58
	v_add_f32_e32 v39, v39, v63
	v_add_f32_e32 v35, v35, v59
	v_add_f32_e32 v40, v40, v64
	v_add_f32_e32 v36, v36, v60
	v_add_f32_e32 v41, v41, v65
	v_add_f32_e32 v37, v37, v61
	v_mul_f32_e32 v38, 0xbfb8aa3b, v38
	v_mul_f32_e32 v34, 0xbfb8aa3b, v34
	v_mul_f32_e32 v39, 0xbfb8aa3b, v39
	v_mul_f32_e32 v35, 0xbfb8aa3b, v35
	v_mul_f32_e32 v40, 0xbfb8aa3b, v40
	v_mul_f32_e32 v36, 0xbfb8aa3b, v36
	v_mul_f32_e32 v41, 0xbfb8aa3b, v41
	v_mul_f32_e32 v37, 0xbfb8aa3b, v37
	v_exp_f32_e32 v38, v38
	v_exp_f32_e32 v34, v34
	v_exp_f32_e32 v39, v39
	v_exp_f32_e32 v35, v35
	v_exp_f32_e32 v40, v40
	v_exp_f32_e32 v36, v36
	v_exp_f32_e32 v41, v41
	v_exp_f32_e32 v37, v37
	v_add_f32_e32 v38, 1.0, v38
	v_add_f32_e32 v34, 1.0, v34
	v_add_f32_e32 v39, 1.0, v39
	v_add_f32_e32 v35, 1.0, v35
	v_add_f32_e32 v40, 1.0, v40
	v_add_f32_e32 v36, 1.0, v36
	v_add_f32_e32 v41, 1.0, v41
	v_add_f32_e32 v37, 1.0, v37
	v_rcp_f32_e32 v38, v38
	v_rcp_f32_e32 v34, v34
	v_rcp_f32_e32 v39, v39
	v_rcp_f32_e32 v35, v35
	v_rcp_f32_e32 v40, v40
	v_rcp_f32_e32 v36, v36
	v_rcp_f32_e32 v41, v41
	v_rcp_f32_e32 v37, v37

; __device__ __forceinline__ float sigmoidf_(float x) { return rcpf_(1.f + ex2(-x * LOG2E)); }
;     __device__ __forceinline__ void operator()(const f32x4 (&acc)[2][2][4][2], const Unit& u, int wr, int wc, int fr, int fq) const {
;     ...
;                 for (int bj = 0; bj < 2; ++bj) { f32x4 v0 = acc[ai][bj][m][0], v1 = acc[ai][bj][m][1];
;                     if (gate) {
; #pragma unroll
;                         for (int j = 0; j < 4; ++j) { v0[j] = sigmoidf_(v0[j] + gb[bj][0][j]); v1[j] = sigmoidf_(v1[j] + gb[bj][1][j]); } }
.LBB0_219:
	v_add_f32_e32 v30, v30, v78
	v_add_f32_e32 v26, v26, v74
	v_add_f32_e32 v31, v31, v79
	v_add_f32_e32 v27, v27, v75
	v_add_f32_e32 v32, v32, v80
	v_add_f32_e32 v28, v28, v76
	v_add_f32_e32 v33, v33, v81
	v_add_f32_e32 v29, v29, v77
	v_mul_f32_e32 v30, 0xbfb8aa3b, v30
	v_mul_f32_e32 v26, 0xbfb8aa3b, v26
	v_mul_f32_e32 v31, 0xbfb8aa3b, v31
	v_mul_f32_e32 v27, 0xbfb8aa3b, v27
	v_mul_f32_e32 v32, 0xbfb8aa3b, v32
	v_mul_f32_e32 v28, 0xbfb8aa3b, v28
	v_mul_f32_e32 v33, 0xbfb8aa3b, v33
	v_mul_f32_e32 v29, 0xbfb8aa3b, v29
	v_exp_f32_e32 v30, v30
	v_exp_f32_e32 v26, v26
	v_exp_f32_e32 v31, v31
	v_exp_f32_e32 v27, v27
	v_exp_f32_e32 v32, v32
	v_exp_f32_e32 v28, v28
	v_exp_f32_e32 v33, v33
	v_exp_f32_e32 v29, v29
	v_add_f32_e32 v30, 1.0, v30
	v_add_f32_e32 v26, 1.0, v26
	v_add_f32_e32 v31, 1.0, v31
	v_add_f32_e32 v27, 1.0, v27
	v_add_f32_e32 v32, 1.0, v32
	v_add_f32_e32 v28, 1.0, v28
	v_add_f32_e32 v33, 1.0, v33
	v_add_f32_e32 v29, 1.0, v29
	v_rcp_f32_e32 v30, v30
	v_rcp_f32_e32 v26, v26
	v_rcp_f32_e32 v31, v31
	v_rcp_f32_e32 v27, v27
	v_rcp_f32_e32 v32, v32
	v_rcp_f32_e32 v28, v28
	v_rcp_f32_e32 v33, v33
	v_rcp_f32_e32 v29, v29

; __device__ __forceinline__ float sigmoidf_(float x) { return rcpf_(1.f + ex2(-x * LOG2E)); }
;     __device__ __forceinline__ void operator()(const f32x4 (&acc)[2][2][4][2], const Unit& u, int wr, int wc, int fr, int fq) const {
;     ...
;                 for (int bj = 0; bj < 2; ++bj) { f32x4 v0 = acc[ai][bj][m][0], v1 = acc[ai][bj][m][1];
;                     if (gate) {
; #pragma unroll
;                         for (int j = 0; j < 4; ++j) { v0[j] = sigmoidf_(v0[j] + gb[bj][0][j]); v1[j] = sigmoidf_(v1[j] + gb[bj][1][j]); } }
.LBB0_222:
	s_andn2_b64 vcc, exec, s[24:25]
	s_cbranch_vccnz .LBB0_224
	v_add_f32_e32 v22, v22, v62
	v_add_f32_e32 v18, v18, v58
	v_add_f32_e32 v23, v23, v63
	v_add_f32_e32 v19, v19, v59
	v_add_f32_e32 v24, v24, v64
	v_add_f32_e32 v20, v20, v60
	v_add_f32_e32 v25, v25, v65
	v_add_f32_e32 v21, v21, v61
	v_mul_f32_e32 v22, 0xbfb8aa3b, v22
	v_mul_f32_e32 v18, 0xbfb8aa3b, v18
	v_mul_f32_e32 v23, 0xbfb8aa3b, v23
	v_mul_f32_e32 v19, 0xbfb8aa3b, v19
	v_mul_f32_e32 v24, 0xbfb8aa3b, v24
	v_mul_f32_e32 v20, 0xbfb8aa3b, v20
	v_mul_f32_e32 v25, 0xbfb8aa3b, v25
	v_mul_f32_e32 v21, 0xbfb8aa3b, v21
	v_exp_f32_e32 v22, v22
	v_exp_f32_e32 v18, v18
	v_exp_f32_e32 v23, v23
	v_exp_f32_e32 v19, v19
	v_exp_f32_e32 v24, v24
	v_exp_f32_e32 v20, v20
	v_exp_f32_e32 v25, v25
	v_exp_f32_e32 v21, v21
	v_add_f32_e32 v22, 1.0, v22
	v_add_f32_e32 v18, 1.0, v18
	v_add_f32_e32 v23, 1.0, v23
	v_add_f32_e32 v19, 1.0, v19
	v_add_f32_e32 v24, 1.0, v24
	v_add_f32_e32 v20, 1.0, v20
	v_add_f32_e32 v25, 1.0, v25
	v_add_f32_e32 v21, 1.0, v21
	v_rcp_f32_e32 v22, v22
	v_rcp_f32_e32 v18, v18
	v_rcp_f32_e32 v23, v23
	v_rcp_f32_e32 v19, v19
	v_rcp_f32_e32 v24, v24
	v_rcp_f32_e32 v20, v20
	v_rcp_f32_e32 v25, v25
	v_rcp_f32_e32 v21, v21

; __device__ __forceinline__ float sigmoidf_(float x) { return rcpf_(1.f + ex2(-x * LOG2E)); }
;     __device__ __forceinline__ void operator()(const f32x4 (&acc)[2][2][4][2], const Unit& u, int wr, int wc, int fr, int fq) const {
;     ...
;                 for (int bj = 0; bj < 2; ++bj) { f32x4 v0 = acc[ai][bj][m][0], v1 = acc[ai][bj][m][1];
;                     if (gate) {
; #pragma unroll
;                         for (int j = 0; j < 4; ++j) { v0[j] = sigmoidf_(v0[j] + gb[bj][0][j]); v1[j] = sigmoidf_(v1[j] + gb[bj][1][j]); } }
.LBB0_231:
	v_add_f32_e32 v14, v14, v78
	v_add_f32_e32 v10, v10, v74
	v_add_f32_e32 v15, v15, v79
	v_add_f32_e32 v11, v11, v75
	v_add_f32_e32 v16, v16, v80
	v_add_f32_e32 v12, v12, v76
	v_add_f32_e32 v17, v17, v81
	v_add_f32_e32 v13, v13, v77
	v_mul_f32_e32 v14, 0xbfb8aa3b, v14
	v_mul_f32_e32 v10, 0xbfb8aa3b, v10
	v_mul_f32_e32 v15, 0xbfb8aa3b, v15
	v_mul_f32_e32 v11, 0xbfb8aa3b, v11
	v_mul_f32_e32 v16, 0xbfb8aa3b, v16
	v_mul_f32_e32 v12, 0xbfb8aa3b, v12
	v_mul_f32_e32 v17, 0xbfb8aa3b, v17
	v_mul_f32_e32 v13, 0xbfb8aa3b, v13
	v_exp_f32_e32 v14, v14
	v_exp_f32_e32 v10, v10
	v_exp_f32_e32 v15, v15
	v_exp_f32_e32 v11, v11
	v_exp_f32_e32 v16, v16
	v_exp_f32_e32 v12, v12
	v_exp_f32_e32 v17, v17
	v_exp_f32_e32 v13, v13
	v_add_f32_e32 v14, 1.0, v14
	v_add_f32_e32 v10, 1.0, v10
	v_add_f32_e32 v15, 1.0, v15
	v_add_f32_e32 v11, 1.0, v11
	v_add_f32_e32 v16, 1.0, v16
	v_add_f32_e32 v12, 1.0, v12
	v_add_f32_e32 v17, 1.0, v17
	v_add_f32_e32 v13, 1.0, v13
	v_rcp_f32_e32 v14, v14
	v_rcp_f32_e32 v10, v10
	v_rcp_f32_e32 v15, v15
	v_rcp_f32_e32 v11, v11
	v_rcp_f32_e32 v16, v16
	v_rcp_f32_e32 v12, v12
	v_rcp_f32_e32 v17, v17
	v_rcp_f32_e32 v13, v13

; __device__ __forceinline__ float sigmoidf_(float x) { return rcpf_(1.f + ex2(-x * LOG2E)); }
;     __device__ __forceinline__ void operator()(const f32x4 (&acc)[2][2][4][2], const Unit& u, int wr, int wc, int fr, int fq) const {
;     ...
;                 for (int bj = 0; bj < 2; ++bj) { f32x4 v0 = acc[ai][bj][m][0], v1 = acc[ai][bj][m][1];
;                     if (gate) {
; #pragma unroll
;                         for (int j = 0; j < 4; ++j) { v0[j] = sigmoidf_(v0[j] + gb[bj][0][j]); v1[j] = sigmoidf_(v1[j] + gb[bj][1][j]); } }
.LBB0_234:
	s_andn2_b64 vcc, exec, s[6:7]
	s_cbranch_vccnz .LBB0_236
	v_add_f32_e32 v6, v6, v62
	v_add_f32_e32 v2, v2, v58
	v_add_f32_e32 v7, v7, v63
	v_add_f32_e32 v3, v3, v59
	v_add_f32_e32 v8, v8, v64
	v_add_f32_e32 v4, v4, v60
	v_add_f32_e32 v9, v9, v65
	v_add_f32_e32 v5, v5, v61
	v_mul_f32_e32 v6, 0xbfb8aa3b, v6
	v_mul_f32_e32 v2, 0xbfb8aa3b, v2
	v_mul_f32_e32 v7, 0xbfb8aa3b, v7
	v_mul_f32_e32 v3, 0xbfb8aa3b, v3
	v_mul_f32_e32 v8, 0xbfb8aa3b, v8
	v_mul_f32_e32 v4, 0xbfb8aa3b, v4
	v_mul_f32_e32 v9, 0xbfb8aa3b, v9
	v_mul_f32_e32 v5, 0xbfb8aa3b, v5
	v_exp_f32_e32 v6, v6
	v_exp_f32_e32 v2, v2
	v_exp_f32_e32 v7, v7
	v_exp_f32_e32 v3, v3
	v_exp_f32_e32 v8, v8
	v_exp_f32_e32 v4, v4
	v_exp_f32_e32 v9, v9
	v_exp_f32_e32 v5, v5
	v_add_f32_e32 v6, 1.0, v6
	v_add_f32_e32 v2, 1.0, v2
	v_add_f32_e32 v7, 1.0, v7
	v_add_f32_e32 v3, 1.0, v3
	v_add_f32_e32 v8, 1.0, v8
	v_add_f32_e32 v4, 1.0, v4
	v_add_f32_e32 v9, 1.0, v9
	v_add_f32_e32 v5, 1.0, v5
	v_rcp_f32_e32 v6, v6
	v_rcp_f32_e32 v2, v2
	v_rcp_f32_e32 v7, v7
	v_rcp_f32_e32 v3, v3
	v_rcp_f32_e32 v8, v8
	v_rcp_f32_e32 v4, v4
	v_rcp_f32_e32 v9, v9
	v_rcp_f32_e32 v5, v5
